# combo23 + scan compute waves at raised issue priority (s_setprio 3) over the staging waves sharing their SIMDs
# baseline (speedup 1.0000x reference)
; #define SC_BAR() do { asm volatile("s_waitcnt lgkmcnt(0)" ::: "memory"); __builtin_amdgcn_s_barrier(); asm volatile("" ::: "memory"); } while (0)
; #define SC_UG(chs) do { const bf16_t* U_ = (const bf16_t*)(p.ws + WS_UT) + (size_t)(chs) * 8192; const float* G_ = (const float*)(p.ws + WS_GB) + (size_t)(chs) * 64; \
;         _Pragma("unroll") for (int tt = 0; tt < 4; ++tt) { u4n[tt] = *(const bf16x4*)(U_ + dv * 64 + 16 * tt + 4 * fq); g4n[tt] = *(const f32x4*)(G_ + 16 * tt + 4 * fq); } \
;         Gln = G_[63]; } while (0)
; template <bool PROMPT>
; __device__ __forceinline__ void scan_block(const Params& p, LAS unsigned char* lds, int chs0, int nsteps, const float* s0, float* sfin, int rowbase, int ntok, int h, int half) {
;     ...
;     bf16_t* CAT = (bf16_t*)(p.ws + WS_CAT);
;     f32x4 ST[8];
; #pragma unroll
;     for (int T = 0; T < 8; ++T)
; #pragma unroll
;         for (int jj = 0; jj < 4; ++jj) ST[T][jj] = s0 ? s0[(size_t)(16 * T + 4 * fq + jj) * 128 + dv] : 0.f;
;     bf16x4 u4n[4]; f32x4 g4n[4]; float Gln;
;     ...
;     SC_UG(chs0);
;     SC_BAR();
.LBB0_600:
	s_andn2_saveexec_b64 s[2:3], s[2:3]
	s_cbranch_execz .LBB0_604
	s_setprio 3
	s_lshl_b32 s1, s33, 6
	s_mov_b32 s5, 0
	s_and_b32 s1, s1, 64
	s_waitcnt vmcnt(0)
	v_lshrrev_b32_e32 v0, 2, v184
	s_lshl_b64 s[6:7], s[4:5], 14
	v_and_b32_e32 v0, 48, v0
	s_add_u32 s10, s50, s6
	v_or3_b32 v160, s1, v0, v128
	s_addc_u32 s11, s51, s7
	s_lshl_b64 s[8:9], s[4:5], 8
	v_bfe_u32 v162, v184, 4, 2
	s_add_u32 s1, s50, s8
	v_mov_b32_e32 v121, 0
	v_lshlrev_b32_e32 v120, 7, v160
	s_addc_u32 s4, s51, s9
	v_lshl_add_u64 v[0:1], s[10:11], 0, v[120:121]
	v_lshlrev_b32_e32 v16, 3, v162
	v_mov_b32_e32 v17, v121
	s_add_u32 s14, s1, 0xd0e8800
	v_lshl_add_u64 v[0:1], v[0:1], 0, v[16:17]
	s_mov_b32 s1, 0xbee8000
	s_addc_u32 s15, s4, 0
	s_mov_b64 s[10:11], 0xbee8800
	v_add_co_u32_e32 v20, vcc, s1, v0
	v_lshlrev_b32_e32 v163, 4, v162
	v_lshl_add_u64 v[18:19], v[0:1], 0, s[10:11]
	v_addc_co_u32_e32 v21, vcc, 0, v1, vcc
	global_load_dwordx4 v[12:15], v163, s[14:15]
	global_load_dwordx4 v[8:11], v163, s[14:15] offset:64
	global_load_dwordx2 v[118:119], v[20:21], off offset:2048
	global_load_dwordx2 v[116:117], v[18:19], off offset:32
	global_load_dwordx2 v[114:115], v[18:19], off offset:64
	global_load_dwordx2 v[112:113], v[18:19], off offset:96
	global_load_dwordx4 v[4:7], v163, s[14:15] offset:128
	global_load_dwordx4 v[0:3], v163, s[14:15] offset:192
	global_load_dword v165, v121, s[14:15] offset:252
	s_movk_i32 s4, 0x110
	v_mov_b32_e32 v17, 0x1100
	v_mad_u32_u24 v168, v128, s4, v17
	v_mov_b32_e32 v17, 0x2200
	v_mad_u32_u24 v167, v128, s4, v17
	v_mov_b32_e32 v17, 0x3300
	v_mad_u32_u24 v166, v128, s4, v17
	s_lshl_b32 s4, s33, 18
	s_lshl_b32 s1, s0, 7
	s_and_b32 s4, s4, 0xe00000
	s_and_b32 s1, s1, 0x180
	v_lshl_or_b32 v17, v162, 12, s4
	v_or3_b32 v17, v17, s1, v160
	v_lshlrev_b32_e32 v17, 1, v17
	v_or_b32_e32 v18, 0x19c00, v17
	v_mov_b32_e32 v19, v121
	s_mov_b64 s[10:11], 0x9b40000
	v_lshl_add_u64 v[122:123], v[18:19], 0, s[10:11]
	v_or_b32_e32 v18, 0x19400, v17
	v_lshl_add_u64 v[124:125], v[18:19], 0, s[10:11]
	v_or_b32_e32 v18, 0x18c00, v17
	v_lshl_add_u64 v[126:127], v[18:19], 0, s[10:11]
	v_or_b32_e32 v18, 0x18400, v17
	v_mul_u32_u24_e32 v169, 0x110, v128
	v_mul_u32_u24_e32 v164, 0x90, v128
	v_lshl_add_u64 v[128:129], v[18:19], 0, s[10:11]
	v_or_b32_e32 v18, 0x11c00, v17
	v_lshl_add_u64 v[130:131], v[18:19], 0, s[10:11]
	v_or_b32_e32 v18, 0x11400, v17
	v_lshl_add_u64 v[132:133], v[18:19], 0, s[10:11]
	v_or_b32_e32 v18, 0x10c00, v17
	v_lshl_add_u64 v[134:135], v[18:19], 0, s[10:11]
	v_or_b32_e32 v18, 0x10400, v17
	v_lshl_add_u64 v[136:137], v[18:19], 0, s[10:11]
	v_or_b32_e32 v18, 0x9c00, v17
	v_lshl_add_u64 v[138:139], v[18:19], 0, s[10:11]
	v_or_b32_e32 v18, 0x9400, v17
	v_lshl_add_u64 v[140:141], v[18:19], 0, s[10:11]
	v_or_b32_e32 v18, 0x8c00, v17
	v_lshl_add_u64 v[142:143], v[18:19], 0, s[10:11]
	v_or_b32_e32 v18, 0x8400, v17
	v_lshl_add_u64 v[144:145], v[18:19], 0, s[10:11]
	v_or_b32_e32 v18, 0x1c00, v17
	v_lshl_add_u64 v[146:147], v[18:19], 0, s[10:11]
	v_or_b32_e32 v18, 0x1400, v17
	s_waitcnt lgkmcnt(0)
	s_barrier
	v_lshl_add_u64 v[148:149], v[18:19], 0, s[10:11]
	v_or_b32_e32 v18, 0xc00, v17
	v_lshl_add_u64 v[150:151], v[18:19], 0, s[10:11]
	v_or_b32_e32 v18, 0x400, v17
	s_add_u32 s4, s8, 0xd0e89fc
	v_or3_b32 v16, s6, v120, v16
	v_mov_b32_e32 v17, s7
	s_mov_b64 s[6:7], 0xbeec840
	v_lshrrev_b32_e32 v161, 4, v184
	v_lshlrev_b32_e32 v170, 2, v162
	v_lshl_add_u64 v[152:153], v[18:19], 0, s[10:11]
	v_or_b32_e32 v154, s8, v163
	v_mov_b32_e32 v155, s9
	s_addc_u32 s14, s9, 0
	v_lshl_add_u64 v[156:157], v[16:17], 0, s[6:7]
	s_mov_b32 s15, 0xd0e8000
	s_mov_b64 s[6:7], 0x20000
	s_mov_b64 s[8:9], 0x100
	s_mov_b64 s[10:11], 0x4000
	v_mov_b32_e32 v32, 0
	v_mov_b32_e32 v33, v121
	v_mov_b32_e32 v34, v121
	v_mov_b32_e32 v35, v121
	v_mov_b32_e32 v36, 0
	v_mov_b32_e32 v37, v121
	v_mov_b32_e32 v38, v121
	v_mov_b32_e32 v39, v121
	v_mov_b32_e32 v40, 0
	v_mov_b32_e32 v41, v121
	v_mov_b32_e32 v42, v121
	v_mov_b32_e32 v43, v121
	v_mov_b32_e32 v44, 0
	v_mov_b32_e32 v45, v121
	v_mov_b32_e32 v46, v121
	v_mov_b32_e32 v47, v121
	v_mov_b32_e32 v16, 0
	v_mov_b32_e32 v17, v121
	v_mov_b32_e32 v18, v121
	v_mov_b32_e32 v20, 0
	v_mov_b32_e32 v21, v121
	v_mov_b32_e32 v22, v121
	v_mov_b32_e32 v23, v121
	v_mov_b32_e32 v24, 0
	v_mov_b32_e32 v25, v121
	v_mov_b32_e32 v26, v121
	v_mov_b32_e32 v27, v121
	v_mov_b32_e32 v28, 0
	v_mov_b32_e32 v29, v121
	v_mov_b32_e32 v30, v121
	v_mov_b32_e32 v31, v121
	s_waitcnt vmcnt(0)
	s_mov_b64 s[96:97], s[50:51]
	s_branch .Lsc_body

; #define LAS __attribute__((address_space(3)))
; template <bool PROMPT>
; __device__ __forceinline__ void scan_block(const Params& p, LAS unsigned char* lds, int chs0, int nsteps, const float* s0, float* sfin, int rowbase, int ntok, int h, int half) {
;     ...
; }
; __device__ __forceinline__ void phase_scan(const Params& p, LAS unsigned char* lds) {
;     if (blockIdx.x < 64) {
;         const int pair = blockIdx.x >> 1, half = blockIdx.x & 1, b = pair >> 2, h = pair & 3;
;         scan_block<true>(p, lds, pair * 32, 32, nullptr, p.out + O_PBS + (size_t)pair * 16384, b * 2048, 64, h, half);
.LBB0_604:
	s_setprio 0
	s_or_b64 exec, exec, s[2:3]
